# gla_out final section: the 2 gain and 8 gate loads of the item issued together after the barrier (were 8 dependent load/compute/store rounds)
# speedup vs baseline: 1.0406x; 1.0032x over previous
.LBB0_760:
	s_or_b64 exec, exec, s[10:11]
	s_lshl_b32 s0, s20, 2
	v_or_b32_e32 v40, s24, v165
	v_mov_b64_e32 v[34:35], s[90:91]
	s_waitcnt lgkmcnt(0)
	v_lshl_add_u64 v[32:33], v[154:155], 0, s[0:1]
	v_mad_i64_i32 v[36:37], s[10:11], v40, s15, v[34:35]
	s_lshl_b32 s0, s20, 1
	v_lshl_add_u64 v[42:43], v[36:37], 0, s[0:1]
	v_lshl_add_u64 v[42:43], v[42:43], 0, v[158:159]
	v_add_co_u32_e32 v44, vcc, s31, v42
	s_nop 1
	v_addc_co_u32_e32 v45, vcc, 0, v43, vcc
	s_barrier
	global_load_dwordx4 v[208:211], v[32:33], off
	global_load_dwordx4 v[212:215], v[32:33], off offset:64
	v_or_b32_e32 v234, s24, v165
	v_mad_i64_i32 v[232:233], s[100:101], v234, s15, v[34:35]
	v_lshl_add_u64 v[232:233], v[232:233], 0, s[0:1]
	v_lshl_add_u64 v[236:237], v[232:233], 0, v[158:159]
	v_add_co_u32_e32 v232, vcc, s31, v236
	s_nop 1
	v_addc_co_u32_e32 v233, vcc, 0, v237, vcc
	global_load_dwordx2 v[216:217], v[232:233], off
	v_lshl_add_u64 v[236:237], v[236:237], 0, s[2:3]
	global_load_dwordx2 v[218:219], v[236:237], off offset:32
	v_or_b32_e32 v234, s24, v171
	v_mad_i64_i32 v[232:233], s[100:101], v234, s15, v[34:35]
	v_lshl_add_u64 v[232:233], v[232:233], 0, s[0:1]
	v_lshl_add_u64 v[236:237], v[232:233], 0, v[158:159]
	v_add_co_u32_e32 v232, vcc, s31, v236
	s_nop 1
	v_addc_co_u32_e32 v233, vcc, 0, v237, vcc
	global_load_dwordx2 v[220:221], v[232:233], off
	v_lshl_add_u64 v[236:237], v[236:237], 0, s[2:3]
	global_load_dwordx2 v[222:223], v[236:237], off offset:32
	v_or_b32_e32 v234, s24, v172
	v_mad_i64_i32 v[232:233], s[100:101], v234, s15, v[34:35]
	v_lshl_add_u64 v[232:233], v[232:233], 0, s[0:1]
	v_lshl_add_u64 v[236:237], v[232:233], 0, v[158:159]
	v_add_co_u32_e32 v232, vcc, s31, v236
	s_nop 1
	v_addc_co_u32_e32 v233, vcc, 0, v237, vcc
	global_load_dwordx2 v[224:225], v[232:233], off
	v_lshl_add_u64 v[236:237], v[236:237], 0, s[2:3]
	global_load_dwordx2 v[226:227], v[236:237], off offset:32
	v_or_b32_e32 v234, s24, v173
	v_mad_i64_i32 v[232:233], s[100:101], v234, s15, v[34:35]
	v_lshl_add_u64 v[232:233], v[232:233], 0, s[0:1]
	v_lshl_add_u64 v[236:237], v[232:233], 0, v[158:159]
	v_add_co_u32_e32 v232, vcc, s31, v236
	s_nop 1
	v_addc_co_u32_e32 v233, vcc, 0, v237, vcc
	global_load_dwordx2 v[228:229], v[232:233], off
	v_lshl_add_u64 v[236:237], v[236:237], 0, s[2:3]
	global_load_dwordx2 v[230:231], v[236:237], off offset:32
	s_mov_b32 s10, 0x358637bd
	ds_read2st64_b32 v[46:47], v178 offset1:1
	ds_read2st64_b32 v[48:49], v178 offset0:2 offset1:3
	ds_read2st64_b32 v[50:51], v178 offset0:4 offset1:5
	ds_read2st64_b32 v[52:53], v178 offset0:6 offset1:7
	ds_read2st64_b32 v[190:191], v180 offset1:1
	ds_read2st64_b32 v[192:193], v180 offset0:2 offset1:3
	ds_read2st64_b32 v[194:195], v180 offset0:4 offset1:5
	ds_read2st64_b32 v[196:197], v180 offset0:6 offset1:7
	s_waitcnt lgkmcnt(7)
	v_mov_b32_e32 v199, v46
	s_waitcnt lgkmcnt(3)
	v_mov_b32_e32 v198, v190
	v_mov_b32_e32 v46, v191
	s_waitcnt lgkmcnt(2)
	v_mov_b32_e32 v190, v192
	v_mov_b32_e32 v191, v48
	v_mov_b32_e32 v48, v193
	s_waitcnt lgkmcnt(1)
	v_mov_b32_e32 v192, v194
	v_mov_b32_e32 v193, v50
	v_mov_b32_e32 v50, v195
	s_waitcnt lgkmcnt(0)
	v_mov_b32_e32 v194, v196
	v_mov_b32_e32 v195, v52
	v_mov_b32_e32 v52, v197
	v_pk_add_f32 v[196:197], v[198:199], 0 op_sel_hi:[1,0]
	v_mov_b32_e32 v54, v28
	v_pk_add_f32 v[46:47], v[196:197], v[46:47]
	v_mov_b32_e32 v55, v30
	v_pk_add_f32 v[46:47], v[46:47], v[190:191]
	v_mov_b32_e32 v30, v29
	v_pk_add_f32 v[46:47], v[46:47], v[48:49]
	v_mov_b64_e32 v[28:29], s[10:11]
	v_pk_add_f32 v[46:47], v[46:47], v[192:193]
	v_lshl_add_u64 v[42:43], v[42:43], 0, s[2:3]
	v_pk_add_f32 v[46:47], v[46:47], v[50:51]
	v_pk_add_f32 v[46:47], v[46:47], v[194:195]
	v_ashrrev_i32_e32 v41, 31, v40
	v_pk_add_f32 v[46:47], v[46:47], v[52:53]
	v_readlane_b32 s20, v253, 61
	v_pk_fma_f32 v[46:47], v[46:47], s[14:15], v[28:29] op_sel_hi:[1,0,0]
	v_lshlrev_b64 v[40:41], 12, v[40:41]
	v_mul_f32_e32 v48, 0x4b800000, v47
	v_cmp_gt_f32_e32 vcc, s35, v47
	v_readlane_b32 s22, v253, 63
	v_readlane_b32 s23, v254, 0
	v_cndmask_b32_e32 v47, v47, v48, vcc
	v_rsq_f32_e32 v47, v47
	v_lshl_add_u64 v[40:41], s[22:23], 0, v[40:41]
	v_lshl_add_u64 v[40:41], v[40:41], 0, s[0:1]
	v_lshl_add_u64 v[40:41], v[40:41], 0, v[158:159]
	v_mul_f32_e32 v48, 0x45800000, v47
	v_cndmask_b32_e32 v48, v47, v48, vcc
	v_pk_mul_f32 v[50:51], v[54:55], v[48:49] op_sel_hi:[1,0]
	v_pk_mul_f32 v[30:31], v[30:31], v[48:49] op_sel_hi:[1,0]
	s_add_i32 s43, s43, s80
	s_cmpk_gt_i32 s43, 0x1ff
	v_readlane_b32 s21, v253, 62
	s_waitcnt vmcnt(0)
	v_mov_b32_e32 v36, v208
	v_mov_b32_e32 v37, v209
	v_mov_b32_e32 v38, v210
	v_mov_b32_e32 v39, v211
	v_mov_b32_e32 v44, v216
	v_mov_b32_e32 v45, v217
	v_mov_b32_e32 v42, v218
	v_mov_b32_e32 v43, v219
	v_mov_b32_e32 v52, v36
	v_mov_b32_e32 v53, v38
	v_mov_b32_e32 v38, v37
	v_lshlrev_b32_e32 v37, 16, v45
	v_lshlrev_b32_e32 v36, 16, v44
	v_and_b32_e32 v45, 0xffff0000, v45
	v_and_b32_e32 v44, 0xffff0000, v44
	v_mul_f32_e32 v47, 0xbfb8aa3b, v36
	v_mul_f32_e32 v54, 0xbfb8aa3b, v37
	v_mul_f32_e32 v49, 0xbfb8aa3b, v44
	v_mul_f32_e32 v55, 0xbfb8aa3b, v45
	v_exp_f32_e32 v47, v47
	v_exp_f32_e32 v54, v54
	v_exp_f32_e32 v49, v49
	v_exp_f32_e32 v55, v55
	v_add_f32_e32 v47, 1.0, v47
	v_add_f32_e32 v157, 1.0, v54
	v_add_f32_e32 v49, 1.0, v49
	v_add_f32_e32 v189, 1.0, v55
	v_rcp_f32_e32 v54, v47
	v_rcp_f32_e32 v55, v157
	v_rcp_f32_e32 v190, v49
	v_rcp_f32_e32 v191, v189
	v_pk_mul_f32 v[50:51], v[52:53], v[50:51]
	v_pk_mul_f32 v[36:37], v[54:55], v[36:37]
	v_pk_mul_f32 v[30:31], v[38:39], v[30:31]
	v_pk_mul_f32 v[38:39], v[190:191], v[44:45]
	v_pk_mul_f32 v[36:37], v[50:51], v[36:37]
	v_pk_mul_f32 v[30:31], v[30:31], v[38:39]
	v_and_b32_sdwa v38, v37, v188 dst_sel:DWORD dst_unused:UNUSED_PAD src0_sel:WORD_1 src1_sel:DWORD
	v_add3_u32 v37, v37, v38, s38
	v_and_b32_sdwa v38, v30, v188 dst_sel:DWORD dst_unused:UNUSED_PAD src0_sel:WORD_1 src1_sel:DWORD
	v_and_b32_sdwa v39, v36, v188 dst_sel:DWORD dst_unused:UNUSED_PAD src0_sel:WORD_1 src1_sel:DWORD
	v_and_b32_sdwa v44, v31, v188 dst_sel:DWORD dst_unused:UNUSED_PAD src0_sel:WORD_1 src1_sel:DWORD
	v_add3_u32 v30, v30, v38, s38
	v_add3_u32 v36, v36, v39, s38
	v_add3_u32 v31, v31, v44, s38
	v_and_b32_e32 v30, 0xffff0000, v30
	v_and_b32_e32 v31, 0xffff0000, v31
	v_or_b32_sdwa v30, v30, v36 dst_sel:DWORD dst_unused:UNUSED_PAD src0_sel:DWORD src1_sel:WORD_1
	v_add_co_u32_e32 v36, vcc, s42, v40
	v_or_b32_sdwa v31, v31, v37 dst_sel:DWORD dst_unused:UNUSED_PAD src0_sel:DWORD src1_sel:WORD_1
	s_nop 0
	v_addc_co_u32_e32 v37, vcc, 0, v41, vcc
	global_store_dwordx2 v[36:37], v[30:31], off offset:2048
	v_mov_b32_e32 v36, v212
	v_mov_b32_e32 v37, v213
	v_mov_b32_e32 v38, v214
	v_mov_b32_e32 v39, v215
	v_lshlrev_b32_e32 v53, 16, v43
	v_lshlrev_b32_e32 v52, 16, v42
	v_and_b32_e32 v43, 0xffff0000, v43
	v_and_b32_e32 v42, 0xffff0000, v42
	v_mov_b32_e32 v30, v24
	v_mov_b32_e32 v31, v26
	v_or_b32_e32 v44, s24, v171
	v_mul_f32_e32 v47, 0xbfb8aa3b, v42
	v_mul_f32_e32 v54, 0xbfb8aa3b, v43
	v_mov_b32_e32 v26, v25
	v_mad_i64_i32 v[24:25], s[10:11], v44, s15, v[34:35]
	v_pk_mul_f32 v[30:31], v[30:31], v[48:49] op_sel_hi:[1,0]
	v_mul_f32_e32 v45, 0xbfb8aa3b, v52
	v_mul_f32_e32 v49, 0xbfb8aa3b, v53
	v_exp_f32_e32 v47, v47
	v_exp_f32_e32 v54, v54
	v_lshl_add_u64 v[24:25], v[24:25], 0, s[0:1]
	v_exp_f32_e32 v45, v45
	v_exp_f32_e32 v49, v49
	v_lshl_add_u64 v[50:51], v[24:25], 0, v[158:159]
	v_add_co_u32_e32 v24, vcc, s31, v50
	v_add_f32_e32 v47, 1.0, v47
	s_nop 0
	v_addc_co_u32_e32 v25, vcc, 0, v51, vcc
	v_add_f32_e32 v157, 1.0, v54
	v_add_f32_e32 v45, 1.0, v45
	v_add_f32_e32 v49, 1.0, v49
	v_rcp_f32_e32 v190, v47
	v_rcp_f32_e32 v191, v157
	v_rcp_f32_e32 v54, v45
	v_rcp_f32_e32 v55, v49
	v_pk_mul_f32 v[24:25], v[26:27], v[48:49] op_sel_hi:[1,0]
	v_pk_mul_f32 v[42:43], v[190:191], v[42:43]
	v_lshl_add_u64 v[40:41], v[40:41], 0, s[12:13]
	v_pk_mul_f32 v[26:27], v[54:55], v[52:53]
	v_ashrrev_i32_e32 v45, 31, v44
	v_cmp_gt_f32_e32 vcc, s35, v46
	v_mov_b32_e32 v192, v220
	v_mov_b32_e32 v193, v221
	v_mov_b32_e32 v49, v38
	v_mov_b32_e32 v38, v37
	v_mov_b32_e32 v48, v36
	v_pk_mul_f32 v[24:25], v[38:39], v[24:25]
	v_pk_mul_f32 v[30:31], v[48:49], v[30:31]
	v_pk_mul_f32 v[24:25], v[24:25], v[42:43]
	v_pk_mul_f32 v[26:27], v[30:31], v[26:27]
	v_and_b32_sdwa v36, v25, v188 dst_sel:DWORD dst_unused:UNUSED_PAD src0_sel:WORD_1 src1_sel:DWORD
	v_and_b32_sdwa v37, v24, v188 dst_sel:DWORD dst_unused:UNUSED_PAD src0_sel:WORD_1 src1_sel:DWORD
	v_and_b32_sdwa v30, v27, v188 dst_sel:DWORD dst_unused:UNUSED_PAD src0_sel:WORD_1 src1_sel:DWORD
	v_and_b32_sdwa v31, v26, v188 dst_sel:DWORD dst_unused:UNUSED_PAD src0_sel:WORD_1 src1_sel:DWORD
	v_add3_u32 v25, v25, v36, s38
	v_add3_u32 v24, v24, v37, s38
	v_add3_u32 v26, v26, v31, s38
	v_add3_u32 v27, v27, v30, s38
	v_and_b32_e32 v25, 0xffff0000, v25
	v_and_b32_e32 v24, 0xffff0000, v24
	v_or_b32_sdwa v25, v25, v27 dst_sel:DWORD dst_unused:UNUSED_PAD src0_sel:DWORD src1_sel:WORD_1
	v_or_b32_sdwa v24, v24, v26 dst_sel:DWORD dst_unused:UNUSED_PAD src0_sel:DWORD src1_sel:WORD_1
	global_store_dwordx2 v[40:41], v[24:25], off offset:32
	v_mov_b32_e32 v30, v20
	v_mov_b32_e32 v31, v22
	v_mov_b32_e32 v22, v21
	v_lshlrev_b64 v[20:21], 12, v[44:45]
	v_lshl_add_u64 v[20:21], s[22:23], 0, v[20:21]
	v_lshl_add_u64 v[20:21], v[20:21], 0, s[0:1]
	v_lshl_add_u64 v[38:39], v[20:21], 0, v[158:159]
	v_mul_f32_e32 v20, 0x4b800000, v46
	v_cndmask_b32_e32 v20, v46, v20, vcc
	v_rsq_f32_e32 v40, v20
	v_lshl_add_u64 v[36:37], v[50:51], 0, s[2:3]
	v_mov_b32_e32 v24, v208
	v_mov_b32_e32 v25, v209
	v_mov_b32_e32 v26, v210
	v_mov_b32_e32 v27, v211
	v_lshlrev_b32_e32 v43, 16, v193
	v_lshlrev_b32_e32 v42, 16, v192
	v_mul_f32_e32 v41, 0x45800000, v40
	v_cndmask_b32_e32 v40, v40, v41, vcc
	v_and_b32_e32 v45, 0xffff0000, v193
	v_and_b32_e32 v44, 0xffff0000, v192
	v_mul_f32_e32 v41, 0xbfb8aa3b, v42
	v_mul_f32_e32 v47, 0xbfb8aa3b, v43
	v_mul_f32_e32 v46, 0xbfb8aa3b, v44
	v_mul_f32_e32 v48, 0xbfb8aa3b, v45
	v_exp_f32_e32 v41, v41
	v_exp_f32_e32 v47, v47
	v_exp_f32_e32 v46, v46
	v_exp_f32_e32 v48, v48
	v_add_f32_e32 v41, 1.0, v41
	v_add_f32_e32 v47, 1.0, v47
	v_add_f32_e32 v49, 1.0, v46
	v_add_f32_e32 v50, 1.0, v48
	v_rcp_f32_e32 v46, v41
	v_rcp_f32_e32 v47, v47
	v_rcp_f32_e32 v48, v49
	v_rcp_f32_e32 v49, v50
	v_pk_mul_f32 v[22:23], v[22:23], v[40:41] op_sel_hi:[1,0]
	v_pk_mul_f32 v[42:43], v[46:47], v[42:43]
	v_pk_mul_f32 v[30:31], v[30:31], v[40:41] op_sel_hi:[1,0]
	v_pk_mul_f32 v[44:45], v[48:49], v[44:45]
	v_add_co_u32_e64 v20, s[10:11], s42, v38
	v_mov_b32_e32 v36, v222
	v_mov_b32_e32 v37, v223
	v_mov_b32_e32 v47, v26
	v_mov_b32_e32 v26, v25
	v_mov_b32_e32 v46, v24
	v_pk_mul_f32 v[22:23], v[26:27], v[22:23]
	v_pk_mul_f32 v[24:25], v[46:47], v[30:31]
	v_pk_mul_f32 v[22:23], v[22:23], v[44:45]
	v_pk_mul_f32 v[24:25], v[24:25], v[42:43]
	v_and_b32_sdwa v30, v23, v188 dst_sel:DWORD dst_unused:UNUSED_PAD src0_sel:WORD_1 src1_sel:DWORD
	v_and_b32_sdwa v31, v22, v188 dst_sel:DWORD dst_unused:UNUSED_PAD src0_sel:WORD_1 src1_sel:DWORD
	v_and_b32_sdwa v26, v25, v188 dst_sel:DWORD dst_unused:UNUSED_PAD src0_sel:WORD_1 src1_sel:DWORD
	v_and_b32_sdwa v27, v24, v188 dst_sel:DWORD dst_unused:UNUSED_PAD src0_sel:WORD_1 src1_sel:DWORD
	v_add3_u32 v23, v23, v30, s38
	v_add3_u32 v22, v22, v31, s38
	v_add3_u32 v24, v24, v27, s38
	v_add3_u32 v25, v25, v26, s38
	v_and_b32_e32 v23, 0xffff0000, v23
	v_and_b32_e32 v22, 0xffff0000, v22
	v_addc_co_u32_e64 v21, s[10:11], 0, v39, s[10:11]
	v_or_b32_sdwa v23, v23, v25 dst_sel:DWORD dst_unused:UNUSED_PAD src0_sel:DWORD src1_sel:WORD_1
	v_or_b32_sdwa v22, v22, v24 dst_sel:DWORD dst_unused:UNUSED_PAD src0_sel:DWORD src1_sel:WORD_1
	global_store_dwordx2 v[20:21], v[22:23], off offset:2048
	v_mov_b32_e32 v24, v16
	v_mov_b32_e32 v25, v18
	v_or_b32_e32 v26, s24, v172
	v_pk_mul_f32 v[24:25], v[24:25], v[40:41] op_sel_hi:[1,0]
	v_mov_b32_e32 v18, v17
	v_mad_i64_i32 v[16:17], s[10:11], v26, s15, v[34:35]
	v_lshl_add_u64 v[16:17], v[16:17], 0, s[0:1]
	v_lshl_add_u64 v[30:31], v[16:17], 0, v[158:159]
	v_add_co_u32_e32 v16, vcc, s31, v30
	v_mov_b32_e32 v20, v212
	v_mov_b32_e32 v21, v213
	v_mov_b32_e32 v22, v214
	v_mov_b32_e32 v23, v215
	v_lshlrev_b32_e32 v43, 16, v37
	v_lshlrev_b32_e32 v42, 16, v36
	v_and_b32_e32 v37, 0xffff0000, v37
	v_and_b32_e32 v36, 0xffff0000, v36
	v_mul_f32_e32 v41, 0xbfb8aa3b, v36
	v_mul_f32_e32 v44, 0xbfb8aa3b, v43
	v_mul_f32_e32 v45, 0xbfb8aa3b, v37
	v_mul_f32_e32 v27, 0xbfb8aa3b, v42
	v_exp_f32_e32 v41, v41
	v_exp_f32_e32 v44, v44
	v_exp_f32_e32 v45, v45
	v_exp_f32_e32 v27, v27
	v_addc_co_u32_e32 v17, vcc, 0, v31, vcc
	v_add_f32_e32 v41, 1.0, v41
	v_add_f32_e32 v47, 1.0, v44
	v_add_f32_e32 v48, 1.0, v45
	v_add_f32_e32 v27, 1.0, v27
	v_rcp_f32_e32 v46, v41
	v_rcp_f32_e32 v45, v47
	v_rcp_f32_e32 v47, v48
	v_rcp_f32_e32 v44, v27
	v_pk_mul_f32 v[16:17], v[18:19], v[40:41] op_sel_hi:[1,0]
	v_pk_mul_f32 v[36:37], v[46:47], v[36:37]
	v_lshl_add_u64 v[38:39], v[38:39], 0, s[12:13]
	v_pk_mul_f32 v[18:19], v[44:45], v[42:43]
	v_lshl_add_u64 v[30:31], v[30:31], 0, s[2:3]
	v_ashrrev_i32_e32 v27, 31, v26
	v_lshlrev_b64 v[26:27], 12, v[26:27]
	v_lshl_add_u64 v[26:27], s[22:23], 0, v[26:27]
	v_lshl_add_u64 v[26:27], v[26:27], 0, s[0:1]
	v_lshl_add_u64 v[26:27], v[26:27], 0, v[158:159]
	v_mov_b32_e32 v48, v224
	v_mov_b32_e32 v49, v225
	v_mov_b32_e32 v41, v22
	v_mov_b32_e32 v22, v21
	v_mov_b32_e32 v40, v20
	v_pk_mul_f32 v[16:17], v[22:23], v[16:17]
	v_pk_mul_f32 v[20:21], v[40:41], v[24:25]
	v_pk_mul_f32 v[16:17], v[16:17], v[36:37]
	v_pk_mul_f32 v[18:19], v[20:21], v[18:19]
	v_and_b32_sdwa v22, v17, v188 dst_sel:DWORD dst_unused:UNUSED_PAD src0_sel:WORD_1 src1_sel:DWORD
	v_and_b32_sdwa v23, v16, v188 dst_sel:DWORD dst_unused:UNUSED_PAD src0_sel:WORD_1 src1_sel:DWORD
	v_and_b32_sdwa v20, v19, v188 dst_sel:DWORD dst_unused:UNUSED_PAD src0_sel:WORD_1 src1_sel:DWORD
	v_and_b32_sdwa v21, v18, v188 dst_sel:DWORD dst_unused:UNUSED_PAD src0_sel:WORD_1 src1_sel:DWORD
	v_add3_u32 v17, v17, v22, s38
	v_add3_u32 v16, v16, v23, s38
	v_add3_u32 v18, v18, v21, s38
	v_add3_u32 v19, v19, v20, s38
	v_and_b32_e32 v17, 0xffff0000, v17
	v_and_b32_e32 v16, 0xffff0000, v16
	v_or_b32_sdwa v17, v17, v19 dst_sel:DWORD dst_unused:UNUSED_PAD src0_sel:DWORD src1_sel:WORD_1
	v_or_b32_sdwa v16, v16, v18 dst_sel:DWORD dst_unused:UNUSED_PAD src0_sel:DWORD src1_sel:WORD_1
	global_store_dwordx2 v[38:39], v[16:17], off offset:32
	ds_read2st64_b32 v[20:21], v181 offset1:1
	ds_read2st64_b32 v[22:23], v181 offset0:2 offset1:3
	ds_read2st64_b32 v[24:25], v181 offset0:4 offset1:5
	ds_read2st64_b32 v[36:37], v181 offset0:6 offset1:7
	v_mov_b32_e32 v38, v12
	v_mov_b32_e32 v39, v14
	v_mov_b32_e32 v14, v13
	ds_read2st64_b32 v[12:13], v182 offset1:1
	ds_read2st64_b32 v[40:41], v182 offset0:2 offset1:3
	ds_read2st64_b32 v[42:43], v182 offset0:4 offset1:5
	ds_read2st64_b32 v[44:45], v182 offset0:6 offset1:7
	s_waitcnt lgkmcnt(7)
	v_mov_b32_e32 v47, v20
	s_waitcnt lgkmcnt(3)
	v_mov_b32_e32 v46, v12
	v_mov_b32_e32 v20, v13
	s_waitcnt lgkmcnt(2)
	v_mov_b32_e32 v12, v40
	v_mov_b32_e32 v13, v22
	v_mov_b32_e32 v22, v41
	s_waitcnt lgkmcnt(1)
	v_mov_b32_e32 v40, v42
	v_mov_b32_e32 v41, v24
	v_mov_b32_e32 v24, v43
	s_waitcnt lgkmcnt(0)
	v_mov_b32_e32 v42, v44
	v_mov_b32_e32 v43, v36
	v_mov_b32_e32 v36, v45
	v_pk_add_f32 v[44:45], v[46:47], 0 op_sel_hi:[1,0]
	s_nop 0
	v_pk_add_f32 v[20:21], v[44:45], v[20:21]
	s_nop 0
	v_pk_add_f32 v[12:13], v[20:21], v[12:13]
	s_nop 0
	v_pk_add_f32 v[12:13], v[12:13], v[22:23]
	s_nop 0
	v_pk_add_f32 v[12:13], v[12:13], v[40:41]
	s_nop 0
	v_pk_add_f32 v[12:13], v[12:13], v[24:25]
	v_pk_add_f32 v[12:13], v[12:13], v[42:43]
	v_mov_b32_e32 v16, v208
	v_mov_b32_e32 v17, v209
	v_mov_b32_e32 v18, v210
	v_mov_b32_e32 v19, v211
	v_mov_b32_e32 v24, v226
	v_mov_b32_e32 v25, v227
	v_and_b32_e32 v31, 0xffff0000, v49
	v_pk_add_f32 v[12:13], v[12:13], v[36:37]
	v_and_b32_e32 v30, 0xffff0000, v48
	v_pk_fma_f32 v[12:13], v[12:13], s[14:15], v[28:29] op_sel_hi:[1,0,0]
	v_lshlrev_b32_e32 v29, 16, v49
	v_mul_f32_e32 v20, 0x4b800000, v13
	v_cmp_gt_f32_e32 vcc, s35, v13
	v_lshlrev_b32_e32 v28, 16, v48
	v_mul_f32_e32 v36, 0xbfb8aa3b, v29
	v_cndmask_b32_e32 v13, v13, v20, vcc
	v_rsq_f32_e32 v13, v13
	v_mul_f32_e32 v23, 0xbfb8aa3b, v30
	v_mul_f32_e32 v37, 0xbfb8aa3b, v31
	v_exp_f32_e32 v36, v36
	v_mul_f32_e32 v22, 0x45800000, v13
	v_cndmask_b32_e32 v22, v13, v22, vcc
	v_mul_f32_e32 v13, 0xbfb8aa3b, v28
	v_exp_f32_e32 v13, v13
	v_exp_f32_e32 v23, v23
	v_exp_f32_e32 v37, v37
	v_add_f32_e32 v41, 1.0, v36
	v_add_f32_e32 v13, 1.0, v13
	v_add_f32_e32 v23, 1.0, v23
	v_add_f32_e32 v42, 1.0, v37
	v_rcp_f32_e32 v36, v13
	v_rcp_f32_e32 v37, v41
	v_rcp_f32_e32 v40, v23
	v_rcp_f32_e32 v41, v42
	v_pk_mul_f32 v[14:15], v[14:15], v[22:23] op_sel_hi:[1,0]
	v_pk_mul_f32 v[28:29], v[36:37], v[28:29]
	v_pk_mul_f32 v[38:39], v[38:39], v[22:23] op_sel_hi:[1,0]
	v_pk_mul_f32 v[30:31], v[40:41], v[30:31]
	v_add_co_u32_e64 v20, s[10:11], s42, v26
	v_mov_b32_e32 v37, v18
	v_mov_b32_e32 v18, v17
	v_mov_b32_e32 v36, v16
	v_pk_mul_f32 v[14:15], v[18:19], v[14:15]
	v_pk_mul_f32 v[16:17], v[36:37], v[38:39]
	v_pk_mul_f32 v[14:15], v[14:15], v[30:31]
	v_pk_mul_f32 v[16:17], v[16:17], v[28:29]
	v_and_b32_sdwa v19, v15, v188 dst_sel:DWORD dst_unused:UNUSED_PAD src0_sel:WORD_1 src1_sel:DWORD
	v_and_b32_sdwa v23, v14, v188 dst_sel:DWORD dst_unused:UNUSED_PAD src0_sel:WORD_1 src1_sel:DWORD
	v_and_b32_sdwa v13, v17, v188 dst_sel:DWORD dst_unused:UNUSED_PAD src0_sel:WORD_1 src1_sel:DWORD
	v_and_b32_sdwa v18, v16, v188 dst_sel:DWORD dst_unused:UNUSED_PAD src0_sel:WORD_1 src1_sel:DWORD
	v_add3_u32 v15, v15, v19, s38
	v_add3_u32 v14, v14, v23, s38
	v_add3_u32 v16, v16, v18, s38
	v_add3_u32 v13, v17, v13, s38
	v_and_b32_e32 v15, 0xffff0000, v15
	v_and_b32_e32 v14, 0xffff0000, v14
	v_addc_co_u32_e64 v21, s[10:11], 0, v27, s[10:11]
	v_or_b32_sdwa v15, v15, v13 dst_sel:DWORD dst_unused:UNUSED_PAD src0_sel:DWORD src1_sel:WORD_1
	v_or_b32_sdwa v14, v14, v16 dst_sel:DWORD dst_unused:UNUSED_PAD src0_sel:DWORD src1_sel:WORD_1
	global_store_dwordx2 v[20:21], v[14:15], off offset:2048
	v_or_b32_e32 v20, s24, v173
	v_mov_b32_e32 v18, v8
	v_mov_b32_e32 v19, v10
	v_mov_b32_e32 v10, v9
	v_mad_i64_i32 v[8:9], s[10:11], v20, s15, v[34:35]
	v_mov_b32_e32 v14, v212
	v_mov_b32_e32 v15, v213
	v_mov_b32_e32 v16, v214
	v_mov_b32_e32 v17, v215
	v_lshlrev_b32_e32 v31, 16, v25
	v_lshlrev_b32_e32 v30, 16, v24
	v_and_b32_e32 v25, 0xffff0000, v25
	v_and_b32_e32 v24, 0xffff0000, v24
	v_mul_f32_e32 v21, 0xbfb8aa3b, v24
	v_mul_f32_e32 v34, 0xbfb8aa3b, v25
	v_exp_f32_e32 v21, v21
	v_exp_f32_e32 v34, v34
	v_pk_mul_f32 v[18:19], v[18:19], v[22:23] op_sel_hi:[1,0]
	v_mul_f32_e32 v13, 0xbfb8aa3b, v30
	v_mul_f32_e32 v23, 0xbfb8aa3b, v31
	v_lshl_add_u64 v[8:9], v[8:9], 0, s[0:1]
	v_exp_f32_e32 v13, v13
	v_exp_f32_e32 v23, v23
	v_lshl_add_u64 v[28:29], v[8:9], 0, v[158:159]
	v_add_co_u32_e32 v8, vcc, s31, v28
	v_add_f32_e32 v21, 1.0, v21
	v_add_f32_e32 v37, 1.0, v34
	v_addc_co_u32_e32 v9, vcc, 0, v29, vcc
	v_rcp_f32_e32 v36, v21
	v_rcp_f32_e32 v37, v37
	v_add_f32_e32 v13, 1.0, v13
	v_add_f32_e32 v23, 1.0, v23
	v_rcp_f32_e32 v34, v13
	v_rcp_f32_e32 v35, v23
	v_pk_mul_f32 v[8:9], v[10:11], v[22:23] op_sel_hi:[1,0]
	v_pk_mul_f32 v[22:23], v[36:37], v[24:25]
	v_lshl_add_u64 v[26:27], v[26:27], 0, s[12:13]
	v_pk_mul_f32 v[10:11], v[34:35], v[30:31]
	v_ashrrev_i32_e32 v21, 31, v20
	v_cmp_gt_f32_e32 vcc, s35, v12
	v_mov_b32_e32 v38, v228
	v_mov_b32_e32 v39, v229
	v_mov_b32_e32 v25, v16
	v_mov_b32_e32 v16, v15
	v_mov_b32_e32 v24, v14
	v_pk_mul_f32 v[8:9], v[16:17], v[8:9]
	v_pk_mul_f32 v[14:15], v[24:25], v[18:19]
	v_pk_mul_f32 v[8:9], v[8:9], v[22:23]
	v_pk_mul_f32 v[10:11], v[14:15], v[10:11]
	v_and_b32_sdwa v15, v9, v188 dst_sel:DWORD dst_unused:UNUSED_PAD src0_sel:WORD_1 src1_sel:DWORD
	v_and_b32_sdwa v16, v8, v188 dst_sel:DWORD dst_unused:UNUSED_PAD src0_sel:WORD_1 src1_sel:DWORD
	v_and_b32_sdwa v13, v11, v188 dst_sel:DWORD dst_unused:UNUSED_PAD src0_sel:WORD_1 src1_sel:DWORD
	v_and_b32_sdwa v14, v10, v188 dst_sel:DWORD dst_unused:UNUSED_PAD src0_sel:WORD_1 src1_sel:DWORD
	v_add3_u32 v9, v9, v15, s38
	v_add3_u32 v8, v8, v16, s38
	v_add3_u32 v10, v10, v14, s38
	v_add3_u32 v11, v11, v13, s38
	v_and_b32_e32 v9, 0xffff0000, v9
	v_and_b32_e32 v8, 0xffff0000, v8
	v_or_b32_sdwa v9, v9, v11 dst_sel:DWORD dst_unused:UNUSED_PAD src0_sel:DWORD src1_sel:WORD_1
	v_or_b32_sdwa v8, v8, v10 dst_sel:DWORD dst_unused:UNUSED_PAD src0_sel:DWORD src1_sel:WORD_1
	global_store_dwordx2 v[26:27], v[8:9], off offset:32
	v_mov_b32_e32 v14, v4
	v_mov_b32_e32 v15, v6
	v_mov_b32_e32 v6, v5
	v_lshlrev_b64 v[4:5], 12, v[20:21]
	v_lshl_add_u64 v[4:5], s[22:23], 0, v[4:5]
	v_lshl_add_u64 v[4:5], v[4:5], 0, s[0:1]
	v_lshl_add_u64 v[18:19], v[4:5], 0, v[158:159]
	v_mul_f32_e32 v4, 0x4b800000, v12
	v_cndmask_b32_e32 v4, v12, v4, vcc
	v_rsq_f32_e32 v12, v4
	v_lshl_add_u64 v[16:17], v[28:29], 0, s[2:3]
	v_mov_b32_e32 v8, v208
	v_mov_b32_e32 v9, v209
	v_mov_b32_e32 v10, v210
	v_mov_b32_e32 v11, v211
	v_lshlrev_b32_e32 v21, 16, v39
	v_lshlrev_b32_e32 v20, 16, v38
	v_mul_f32_e32 v13, 0x45800000, v12
	v_cndmask_b32_e32 v12, v12, v13, vcc
	v_and_b32_e32 v23, 0xffff0000, v39
	v_and_b32_e32 v22, 0xffff0000, v38
	v_mul_f32_e32 v13, 0xbfb8aa3b, v20
	v_mul_f32_e32 v25, 0xbfb8aa3b, v21
	v_mul_f32_e32 v24, 0xbfb8aa3b, v22
	v_mul_f32_e32 v26, 0xbfb8aa3b, v23
	v_exp_f32_e32 v13, v13
	v_exp_f32_e32 v25, v25
	v_exp_f32_e32 v24, v24
	v_exp_f32_e32 v26, v26
	v_add_f32_e32 v13, 1.0, v13
	v_add_f32_e32 v25, 1.0, v25
	v_add_f32_e32 v27, 1.0, v24
	v_add_f32_e32 v28, 1.0, v26
	v_rcp_f32_e32 v24, v13
	v_rcp_f32_e32 v25, v25
	v_rcp_f32_e32 v26, v27
	v_rcp_f32_e32 v27, v28
	v_pk_mul_f32 v[6:7], v[6:7], v[12:13] op_sel_hi:[1,0]
	v_pk_mul_f32 v[20:21], v[24:25], v[20:21]
	v_pk_mul_f32 v[14:15], v[14:15], v[12:13] op_sel_hi:[1,0]
	v_pk_mul_f32 v[22:23], v[26:27], v[22:23]
	v_add_co_u32_e64 v4, s[10:11], s42, v18
	v_mov_b32_e32 v16, v230
	v_mov_b32_e32 v17, v231
	v_mov_b32_e32 v25, v10
	v_mov_b32_e32 v10, v9
	v_mov_b32_e32 v24, v8
	v_pk_mul_f32 v[6:7], v[10:11], v[6:7]
	v_pk_mul_f32 v[8:9], v[24:25], v[14:15]
	v_pk_mul_f32 v[6:7], v[6:7], v[22:23]
	v_pk_mul_f32 v[8:9], v[8:9], v[20:21]
	v_and_b32_sdwa v13, v7, v188 dst_sel:DWORD dst_unused:UNUSED_PAD src0_sel:WORD_1 src1_sel:DWORD
	v_and_b32_sdwa v14, v6, v188 dst_sel:DWORD dst_unused:UNUSED_PAD src0_sel:WORD_1 src1_sel:DWORD
	v_and_b32_sdwa v10, v9, v188 dst_sel:DWORD dst_unused:UNUSED_PAD src0_sel:WORD_1 src1_sel:DWORD
	v_and_b32_sdwa v11, v8, v188 dst_sel:DWORD dst_unused:UNUSED_PAD src0_sel:WORD_1 src1_sel:DWORD
	v_add3_u32 v7, v7, v13, s38
	v_add3_u32 v6, v6, v14, s38
	v_add3_u32 v8, v8, v11, s38
	v_add3_u32 v9, v9, v10, s38
	v_and_b32_e32 v7, 0xffff0000, v7
	v_and_b32_e32 v6, 0xffff0000, v6
	v_addc_co_u32_e64 v5, s[10:11], 0, v19, s[10:11]
	v_or_b32_sdwa v7, v7, v9 dst_sel:DWORD dst_unused:UNUSED_PAD src0_sel:DWORD src1_sel:WORD_1
	v_or_b32_sdwa v6, v6, v8 dst_sel:DWORD dst_unused:UNUSED_PAD src0_sel:DWORD src1_sel:WORD_1
	global_store_dwordx2 v[4:5], v[6:7], off offset:2048
	v_mov_b32_e32 v8, v0
	v_mov_b32_e32 v9, v2
	v_mov_b32_e32 v2, v1
	v_lshl_add_u64 v[0:1], v[18:19], 0, s[12:13]
	v_mov_b32_e32 v4, v212
	v_mov_b32_e32 v5, v213
	v_mov_b32_e32 v6, v214
	v_mov_b32_e32 v7, v215
	v_and_b32_e32 v15, 0xffff0000, v17
	v_and_b32_e32 v14, 0xffff0000, v16
	v_lshlrev_b32_e32 v10, 16, v16
	v_mul_f32_e32 v16, 0xbfb8aa3b, v14
	v_mul_f32_e32 v18, 0xbfb8aa3b, v15
	v_lshlrev_b32_e32 v11, 16, v17
	v_exp_f32_e32 v16, v16
	v_exp_f32_e32 v18, v18
	v_mul_f32_e32 v13, 0xbfb8aa3b, v10
	v_mul_f32_e32 v17, 0xbfb8aa3b, v11
	v_exp_f32_e32 v13, v13
	v_exp_f32_e32 v17, v17
	v_add_f32_e32 v19, 1.0, v16
	v_add_f32_e32 v20, 1.0, v18
	v_rcp_f32_e32 v18, v19
	v_rcp_f32_e32 v19, v20
	v_add_f32_e32 v13, 1.0, v13
	v_add_f32_e32 v17, 1.0, v17
	v_rcp_f32_e32 v16, v13
	v_rcp_f32_e32 v17, v17
	v_pk_mul_f32 v[8:9], v[8:9], v[12:13] op_sel_hi:[1,0]
	v_pk_mul_f32 v[2:3], v[2:3], v[12:13] op_sel_hi:[1,0]
	v_pk_mul_f32 v[12:13], v[18:19], v[14:15]
	v_pk_mul_f32 v[10:11], v[16:17], v[10:11]
	v_mov_b32_e32 v15, v6
	v_mov_b32_e32 v6, v5
	v_mov_b32_e32 v14, v4
	v_pk_mul_f32 v[2:3], v[6:7], v[2:3]
	v_pk_mul_f32 v[4:5], v[14:15], v[8:9]
	v_pk_mul_f32 v[2:3], v[2:3], v[12:13]
	v_pk_mul_f32 v[4:5], v[4:5], v[10:11]
	v_and_b32_sdwa v8, v3, v188 dst_sel:DWORD dst_unused:UNUSED_PAD src0_sel:WORD_1 src1_sel:DWORD
	v_and_b32_sdwa v9, v2, v188 dst_sel:DWORD dst_unused:UNUSED_PAD src0_sel:WORD_1 src1_sel:DWORD
	v_and_b32_sdwa v6, v5, v188 dst_sel:DWORD dst_unused:UNUSED_PAD src0_sel:WORD_1 src1_sel:DWORD
	v_and_b32_sdwa v7, v4, v188 dst_sel:DWORD dst_unused:UNUSED_PAD src0_sel:WORD_1 src1_sel:DWORD
	v_add3_u32 v3, v3, v8, s38
	v_add3_u32 v2, v2, v9, s38
	v_add3_u32 v4, v4, v7, s38
	v_add3_u32 v5, v5, v6, s38
	v_and_b32_e32 v3, 0xffff0000, v3
	v_and_b32_e32 v2, 0xffff0000, v2
	v_or_b32_sdwa v3, v3, v5 dst_sel:DWORD dst_unused:UNUSED_PAD src0_sel:DWORD src1_sel:WORD_1
	v_or_b32_sdwa v2, v2, v4 dst_sel:DWORD dst_unused:UNUSED_PAD src0_sel:DWORD src1_sel:WORD_1
	global_store_dwordx2 v[0:1], v[2:3], off offset:32
	s_barrier
	s_cbranch_scc1 .LBB0_781
